# M1: XOR swizzle of the transposed K^T/V^T LDS tiles (16-way bank conflict on the transposing ds_write_b32 removed); delta-C stage with swizzled fragment reads
# speedup vs baseline: 1.0096x; 1.0096x over previous
.LBB0_360:
	s_or_b64 exec, exec, s[0:1]
	v_ashrrev_i32_e32 v38, 2, v2
	v_lshrrev_b32_e32 v35, 1, v2
	v_bfi_b32 v34, -16, v38, v2
	v_and_b32_e32 v42, 24, v35
	v_mul_lo_u32 v34, v34, s36
	v_and_b32_e32 v3, 15, v2
	v_lshrrev_b32_e32 v202, 3, v2
	v_and_b32_e32 v203, 1, v202
	v_lshrrev_b32_e32 v204, 5, v2
	v_and_b32_e32 v204, 6, v204
	v_or_b32_e32 v204, v204, v203
	v_lshrrev_b32_e32 v205, 3, v42
	v_xor_b32_e32 v204, v205, v204
	v_lshl_add_u32 v206, v204, 4, v34
	v_xor_b32_e32 v204, 4, v204
	v_lshl_add_u32 v207, v204, 4, v34
	ds_read_b128 v[130:133], v206
	ds_read_b128 v[134:137], v207
	v_mul_u32_u24_e32 v34, 0x90, v3
	v_xor_b32_e32 v208, v205, v203
	v_lshl_add_u32 v110, v208, 4, v34
	v_xor_b32_e32 v208, 2, v208
	v_lshl_add_u32 v209, v208, 4, v34
	v_lshlrev_b32_e32 v35, 1, v42
	ds_read_b128 v[138:141], v110 offset:18432
	ds_read_b128 v[142:145], v110 offset:18496
	ds_read_b128 v[146:149], v209 offset:20736
	ds_read_b128 v[150:153], v209 offset:20800
	ds_read_b128 v[154:157], v110 offset:23104
	ds_read_b128 v[158:161], v110 offset:23040
	ds_read_b128 v[162:165], v209 offset:25408
	ds_read_b128 v[166:169], v209 offset:25344
	ds_read_b128 v[170:173], v110 offset:27648
	ds_read_b128 v[174:177], v110 offset:27712
	ds_read_b128 v[178:181], v209 offset:29952
	ds_read_b128 v[182:185], v209 offset:30016
	ds_read_b128 v[186:189], v110 offset:32320
	ds_read_b128 v[190:193], v110 offset:32256
	ds_read_b128 v[194:197], v209 offset:34624
	ds_read_b128 v[198:201], v209 offset:34560
	v_and_b32_e32 v43, -16, v38
	v_lshl_add_u32 v43, v43, 1, s41
	v_mul_u32_u24_e32 v3, 0x110, v3
	v_add3_u32 v111, v43, v42, v3
	s_waitcnt lgkmcnt(15)
	v_mfma_f32_16x16x32_bf16 v[138:141], v[130:133], v[138:141], 0
	s_waitcnt lgkmcnt(13)
	v_mfma_f32_16x16x32_bf16 v[146:149], v[130:133], v[146:149], 0
	s_waitcnt lgkmcnt(11)
	v_mfma_f32_16x16x32_bf16 v[154:157], v[130:133], v[154:157], 0
	s_waitcnt lgkmcnt(9)
	v_mfma_f32_16x16x32_bf16 v[162:165], v[130:133], v[162:165], 0
	s_waitcnt lgkmcnt(7)
	v_mfma_f32_16x16x32_bf16 v[170:173], v[130:133], v[170:173], 0
	s_waitcnt lgkmcnt(5)
	v_mfma_f32_16x16x32_bf16 v[178:181], v[130:133], v[178:181], 0
	s_waitcnt lgkmcnt(3)
	v_mfma_f32_16x16x32_bf16 v[186:189], v[130:133], v[186:189], 0
	s_waitcnt lgkmcnt(1)
	v_mfma_f32_16x16x32_bf16 v[194:197], v[130:133], v[194:197], 0
	s_waitcnt lgkmcnt(0)
	v_mfma_f32_16x16x32_bf16 v[138:141], v[134:137], v[142:145], v[138:141]
	v_mfma_f32_16x16x32_bf16 v[146:149], v[134:137], v[150:153], v[146:149]
	v_mfma_f32_16x16x32_bf16 v[154:157], v[134:137], v[158:161], v[154:157]
	v_mfma_f32_16x16x32_bf16 v[162:165], v[134:137], v[166:169], v[162:165]
	v_mfma_f32_16x16x32_bf16 v[170:173], v[134:137], v[174:177], v[170:173]
	v_mfma_f32_16x16x32_bf16 v[178:181], v[134:137], v[182:185], v[178:181]
	v_mfma_f32_16x16x32_bf16 v[186:189], v[134:137], v[190:193], v[186:189]
	v_mfma_f32_16x16x32_bf16 v[194:197], v[134:137], v[198:201], v[194:197]
	v_cvt_pk_bf16_f32 v142, v138, v139
	v_cvt_pk_bf16_f32 v143, v140, v141
	ds_write_b64 v111, v[142:143]
	v_cvt_pk_bf16_f32 v150, v146, v147
	v_cvt_pk_bf16_f32 v151, v148, v149
	ds_write_b64 v111, v[150:151] offset:4352
	v_cvt_pk_bf16_f32 v158, v154, v155
	v_cvt_pk_bf16_f32 v159, v156, v157
	ds_write_b64 v111, v[158:159] offset:8704
	v_cvt_pk_bf16_f32 v166, v162, v163
	v_cvt_pk_bf16_f32 v167, v164, v165
	ds_write_b64 v111, v[166:167] offset:13056
	v_cvt_pk_bf16_f32 v174, v170, v171
	v_cvt_pk_bf16_f32 v175, v172, v173
	ds_write_b64 v111, v[174:175] offset:17408
	v_cvt_pk_bf16_f32 v182, v178, v179
	v_cvt_pk_bf16_f32 v183, v180, v181
	ds_write_b64 v111, v[182:183] offset:21760
	v_cvt_pk_bf16_f32 v190, v186, v187
	v_cvt_pk_bf16_f32 v191, v188, v189
	ds_write_b64 v111, v[190:191] offset:26112
	v_cvt_pk_bf16_f32 v198, v194, v195
	v_cvt_pk_bf16_f32 v199, v196, v197
	ds_write_b64 v111, v[198:199] offset:30464
	v_lshlrev_b64 v[62:63], 15, v[32:33]
	v_lshlrev_b32_e32 v98, 1, v85
	v_add_u32_e32 v85, 0x200, v2
	v_add_u32_e32 v102, 0x400, v2
	v_add_u32_e32 v103, 0x600, v2
	s_nop 2
	v_mov_b32_e32 v99, v0
	v_lshlrev_b32_e32 v100, 7, v84
	v_ashrrev_i32_e32 v106, 4, v102
	v_ashrrev_i32_e32 v103, 4, v103
	s_add_u32 s22, s22, s12
	s_addc_u32 s23, s23, s13
	v_ashrrev_i32_e32 v101, 31, v100
	s_add_i32 s20, s20, s40
	s_nop 2
	v_lshlrev_b32_e32 v108, 7, v103
	s_add_u32 s24, s24, s26
	v_ashrrev_i32_e32 v109, 31, v108
	s_waitcnt vmcnt(2)
	v_mov_b64_e32 v[34:35], v[30:31]
	v_mov_b64_e32 v[38:39], v[26:27]
	v_mov_b64_e32 v[46:47], v[22:23]
	v_mov_b64_e32 v[54:55], v[18:19]
	v_mov_b64_e32 v[50:51], v[14:15]
	s_nop 1
	v_lshl_add_u64 v[2:3], s[80:81], 0, v[62:63]
	v_add_u32_e32 v62, s41, v98
	v_ashrrev_i32_e32 v63, 4, v85
	v_mad_u64_u32 v[84:85], s[0:1], v84, s37, v[62:63]
	v_lshl_add_u64 v[2:3], v[2:3], 0, v[98:99]
	v_mad_u64_u32 v[98:99], s[0:1], v63, s37, v[62:63]
	v_lshlrev_b32_e32 v102, 7, v63
	s_nop 3
	v_mad_u64_u32 v[104:105], s[0:1], v106, s37, v[62:63]
	v_mad_u64_u32 v[62:63], s[0:1], v103, s37, v[62:63]
	v_lshlrev_b32_e32 v106, 7, v106
	v_lshl_add_u64 v[100:101], v[100:101], 1, v[2:3]
	v_ashrrev_i32_e32 v103, 31, v102
	v_ashrrev_i32_e32 v107, 31, v106
	v_mov_b64_e32 v[42:43], v[6:7]
	s_nop 2
	s_addc_u32 s25, s25, s27
	v_lshl_add_u64 v[102:103], v[102:103], 1, v[2:3]
	v_lshl_add_u64 v[106:107], v[106:107], 1, v[2:3]
	v_lshl_add_u64 v[2:3], v[108:109], 1, v[2:3]
	s_waitcnt vmcnt(0)
	v_mov_b32_e32 v60, v65
	v_mov_b32_e32 v61, v1
	v_mov_b64_e32 v[32:33], v[28:29]
	v_mov_b64_e32 v[36:37], v[24:25]
	s_nop 1
	v_mov_b64_e32 v[44:45], v[20:21]
	v_mov_b64_e32 v[52:53], v[16:17]
	v_mov_b64_e32 v[48:49], v[12:13]
	v_mov_b64_e32 v[40:41], v[4:5]
	s_cmpk_lt_i32 s22, 0x800
	s_nop 5
	s_nop 7
	s_waitcnt lgkmcnt(0)
	s_barrier
	ds_read_b128 v[56:59], v84
	ds_read_b128 v[84:87], v98
	ds_read_b128 v[88:91], v104
	ds_read_b128 v[92:95], v62
	s_waitcnt lgkmcnt(3)
	global_store_dwordx4 v[100:101], v[56:59], off
	s_waitcnt lgkmcnt(2)
	global_store_dwordx4 v[102:103], v[84:87], off
	s_waitcnt lgkmcnt(1)
	global_store_dwordx4 v[106:107], v[88:91], off
	s_waitcnt lgkmcnt(0)
	global_store_dwordx4 v[2:3], v[92:95], off
	v_mov_b64_e32 v[58:59], v[10:11]
	v_mov_b64_e32 v[56:57], v[8:9]
	s_cbranch_scc0 .LBB0_378

.LBB0_374:
	s_or_b64 exec, exec, s[2:3]
	v_lshlrev_b32_e32 v60, 3, v2
	s_and_b32 s0, s20, 0x180
	v_and_b32_e32 v85, 0x78, v60
	s_lshl_b32 s0, s0, 2
	s_add_i32 s0, s0, 0
	v_lshlrev_b32_e32 v114, 2, v85
	v_add_u32_e32 v60, s0, v114
	v_add_u32_e32 v110, 0x10800, v60
	ds_read_b128 v[86:89], v110
	ds_read_b128 v[60:63], v110 offset:16
	ds_read_b128 v[90:93], v110 offset:4096
	ds_read_b128 v[94:97], v110 offset:8192
	ds_read_b128 v[98:101], v110 offset:12288
	v_lshlrev_b32_e32 v117, 16, v41
	v_and_b32_e32 v41, 0xffff0000, v41
	v_lshlrev_b32_e32 v115, 16, v57
	v_and_b32_e32 v57, 0xffff0000, v57
	s_waitcnt lgkmcnt(2)
	v_mul_f32_e32 v128, v93, v41
	v_lshlrev_b32_e32 v119, 16, v49
	v_and_b32_e32 v49, 0xffff0000, v49
	v_fmac_f32_e32 v128, v89, v57
	v_lshlrev_b32_e32 v121, 16, v53
	v_and_b32_e32 v53, 0xffff0000, v53
	s_waitcnt lgkmcnt(1)
	v_fmac_f32_e32 v128, v97, v49
	s_waitcnt lgkmcnt(0)
	v_fmac_f32_e32 v128, v101, v53
	v_mul_f32_e32 v57, 0xbfb8aa3b, v128
	v_exp_f32_e32 v57, v57
	v_lshlrev_b32_e32 v116, 16, v40
	v_and_b32_e32 v40, 0xffff0000, v40
	v_lshlrev_b32_e32 v118, 16, v48
	v_lshlrev_b32_e32 v106, 16, v56
	v_and_b32_e32 v56, 0xffff0000, v56
	v_mul_f32_e32 v123, v90, v116
	v_mul_f32_e32 v126, v91, v40
	v_add_f32_e32 v57, 1.0, v57
	v_mul_f32_e32 v90, v90, v118
	v_and_b32_e32 v48, 0xffff0000, v48
	v_lshlrev_b32_e32 v120, 16, v52
	v_fmac_f32_e32 v126, v87, v56
	v_rcp_f32_e32 v57, v57
	v_fmac_f32_e32 v90, v86, v116
	v_lshlrev_b32_e32 v122, 16, v44
	v_fmac_f32_e32 v126, v95, v48
	v_fmac_f32_e32 v90, v94, v120
	v_mul_f32_e32 v48, v91, v48
	v_and_b32_e32 v52, 0xffff0000, v52
	v_fmac_f32_e32 v90, v98, v122
	v_fmac_f32_e32 v48, v87, v40
	v_fmac_f32_e32 v123, v86, v106
	v_and_b32_e32 v44, 0xffff0000, v44
	v_mul_f32_e32 v86, 0xbfb8aa3b, v90
	v_fmac_f32_e32 v48, v95, v52
	v_exp_f32_e32 v86, v86
	v_fmac_f32_e32 v48, v99, v44
	v_mul_f32_e32 v44, v128, v57
	v_mul_f32_e32 v57, v92, v119
	v_fmac_f32_e32 v57, v88, v117
	v_lshlrev_b32_e32 v125, 16, v45
	v_fmac_f32_e32 v57, v96, v121
	v_fmac_f32_e32 v57, v100, v125
	v_fmac_f32_e32 v126, v99, v52
	v_add_f32_e32 v52, 1.0, v86
	v_mul_f32_e32 v86, 0xbfb8aa3b, v57
	v_exp_f32_e32 v86, v86
	v_mul_f32_e32 v49, v93, v49
	v_fmac_f32_e32 v49, v89, v41
	v_and_b32_e32 v45, 0xffff0000, v45
	v_fmac_f32_e32 v49, v97, v53
	v_fmac_f32_e32 v49, v101, v45
	v_add_f32_e32 v45, 1.0, v86
	ds_read_b128 v[102:105], v110 offset:4112
	ds_read_b128 v[106:109], v110 offset:8208
	v_rcp_f32_e32 v45, v45
	v_mul_f32_e32 v40, 0xbfb8aa3b, v48
	v_mul_f32_e32 v41, 0xbfb8aa3b, v49
	v_exp_f32_e32 v40, v40
	v_exp_f32_e32 v41, v41
	ds_read_b128 v[110:113], v110 offset:12304
	v_mul_f32_e32 v45, v57, v45
	v_lshlrev_b32_e32 v53, 16, v59
	v_and_b32_e32 v57, 0xffff0000, v59
	v_lshlrev_b32_e32 v59, 16, v43
	v_and_b32_e32 v43, 0xffff0000, v43
	s_waitcnt lgkmcnt(2)
	v_mul_f32_e32 v95, v105, v43
	v_add_f32_e32 v40, 1.0, v40
	v_add_f32_e32 v41, 1.0, v41
	v_lshlrev_b32_e32 v87, 16, v51
	v_and_b32_e32 v51, 0xffff0000, v51
	v_fmac_f32_e32 v95, v63, v57
	v_rcp_f32_e32 v40, v40
	v_rcp_f32_e32 v41, v41
	v_lshlrev_b32_e32 v89, 16, v55
	v_and_b32_e32 v55, 0xffff0000, v55
	s_waitcnt lgkmcnt(1)
	v_fmac_f32_e32 v95, v109, v51
	s_waitcnt lgkmcnt(0)
	v_fmac_f32_e32 v95, v113, v55
	v_mul_f32_e32 v57, 0xbfb8aa3b, v95
	v_exp_f32_e32 v57, v57
	v_mul_f32_e32 v40, v48, v40
	v_mul_f32_e32 v41, v49, v41
	v_lshlrev_b32_e32 v48, 16, v58
	v_and_b32_e32 v49, 0xffff0000, v58
	v_lshlrev_b32_e32 v58, 16, v42
	v_rcp_f32_e32 v52, v52
	v_mul_f32_e32 v91, v102, v58
	v_and_b32_e32 v42, 0xffff0000, v42
	v_lshlrev_b32_e32 v86, 16, v50
	v_fmac_f32_e32 v91, v60, v48
	v_mul_f32_e32 v127, v92, v117
	v_fmac_f32_e32 v91, v106, v86
	v_mul_f32_e32 v93, v103, v42
	v_add_f32_e32 v57, 1.0, v57
	v_mul_f32_e32 v86, v102, v86
	v_fmac_f32_e32 v127, v88, v115
	v_and_b32_e32 v50, 0xffff0000, v50
	v_lshlrev_b32_e32 v88, 16, v54
	v_fmac_f32_e32 v93, v61, v49
	v_rcp_f32_e32 v57, v57
	v_fmac_f32_e32 v86, v60, v58
	v_mul_f32_e32 v52, v90, v52
	v_lshlrev_b32_e32 v90, 16, v46
	v_fmac_f32_e32 v93, v107, v50
	v_fmac_f32_e32 v86, v106, v88
	v_mul_f32_e32 v50, v103, v50
	v_and_b32_e32 v54, 0xffff0000, v54
	v_fmac_f32_e32 v86, v110, v90
	v_fmac_f32_e32 v50, v61, v42
	v_and_b32_e32 v46, 0xffff0000, v46
	v_mul_f32_e32 v58, 0xbfb8aa3b, v86
	v_fmac_f32_e32 v50, v107, v54
	v_exp_f32_e32 v58, v58
	v_fmac_f32_e32 v50, v111, v46
	v_mul_f32_e32 v46, v95, v57
	v_mul_f32_e32 v57, v104, v87
	v_fmac_f32_e32 v57, v62, v59
	v_fmac_f32_e32 v123, v94, v118
	v_lshlrev_b32_e32 v92, 16, v47
	v_fmac_f32_e32 v57, v108, v89
	v_fmac_f32_e32 v123, v98, v120
	v_fmac_f32_e32 v57, v112, v92
	v_mul_f32_e32 v124, 0xbfb8aa3b, v123
	v_fmac_f32_e32 v93, v111, v54
	v_add_f32_e32 v54, 1.0, v58
	v_mul_f32_e32 v58, 0xbfb8aa3b, v57
	v_exp_f32_e32 v124, v124
	v_exp_f32_e32 v58, v58
	v_mul_f32_e32 v42, 0xbfb8aa3b, v50
	v_mul_f32_e32 v51, v105, v51
	v_ashrrev_i32_e32 v84, 4, v2
	v_mul_f32_e32 v56, 0xbfb8aa3b, v126
	v_mul_f32_e32 v94, v104, v59
	v_exp_f32_e32 v42, v42
	v_fmac_f32_e32 v51, v63, v43
	v_exp_f32_e32 v56, v56
	v_fmac_f32_e32 v127, v96, v119
	v_and_b32_e32 v47, 0xffff0000, v47
	v_fmac_f32_e32 v94, v62, v53
	v_fmac_f32_e32 v51, v109, v55
	v_lshl_add_u32 v62, v84, 3, 0
	v_add_f32_e32 v124, 1.0, v124
	v_fmac_f32_e32 v127, v100, v121
	v_fmac_f32_e32 v51, v113, v47
	v_add_f32_e32 v47, 1.0, v58
	v_lshlrev_b32_e32 v58, 16, v32
	v_and_b32_e32 v59, 0xffff0000, v32
	v_lshlrev_b32_e32 v60, 16, v33
	v_and_b32_e32 v61, 0xffff0000, v33
	s_barrier
	ds_read_b64 v[32:33], v62 offset:36864
	v_mul_f32_e32 v115, 0xbfb8aa3b, v127
	v_rcp_f32_e32 v124, v124
	v_exp_f32_e32 v115, v115
	v_add_f32_e32 v42, 1.0, v42
	v_add_f32_e32 v56, 1.0, v56
	v_rcp_f32_e32 v42, v42
	v_rcp_f32_e32 v56, v56
	v_mul_f32_e32 v43, 0xbfb8aa3b, v51
	v_mul_f32_e32 v123, v123, v124
	v_fmac_f32_e32 v94, v108, v87
	v_exp_f32_e32 v43, v43
	s_waitcnt lgkmcnt(0)
	v_mul_f32_e32 v32, 0x3db504f3, v32
	v_mul_f32_e32 v33, 0x3db504f3, v33
	v_lshlrev_b32_e32 v87, 2, v84
	v_add_f32_e32 v115, 1.0, v115
	v_fmac_f32_e32 v91, v110, v88
	v_fmac_f32_e32 v94, v112, v89
	v_sub_u32_e32 v62, v62, v87
	v_lshlrev_b32_e32 v87, 9, v84
	v_mul_f32_e32 v88, v123, v32
	v_mul_f32_e32 v52, v52, v33
	v_mul_u32_u24_e32 v89, 0x48, v85
	v_rcp_f32_e32 v115, v115
	v_mul_f32_e32 v48, 0xbfb8aa3b, v91
	v_mul_f32_e32 v42, v50, v42
	v_lshlrev_b32_e32 v50, 16, v36
	v_add3_u32 v87, 0, v114, v87
	v_cvt_pk_bf16_f32 v88, v88, v52
	v_lshrrev_b32_e32 v130, 2, v84
	v_and_b32_e32 v131, 7, v2
	v_xor_b32_e32 v130, v130, v131
	v_and_b32_e32 v131, 3, v84
	v_lshlrev_b32_e32 v131, 2, v131
	v_lshl_or_b32 v130, v130, 4, v131
	v_lshl_add_u32 v62, v89, 1, v130
	v_fmac_f32_e32 v52, v123, v32
	v_mul_f32_e32 v56, v126, v56
	v_exp_f32_e32 v48, v48
	ds_write_b32 v62, v88
	ds_write_b32 v87, v52 offset:37120
	v_cvt_pk_bf16_f32 v50, v50, v58
	v_add_f32_e32 v43, 1.0, v43
	ds_write_b32 v62, v50 offset:18432
	v_mul_f32_e32 v50, v56, v32
	v_mul_f32_e32 v40, v40, v33
	v_mul_f32_e32 v49, 0xbfb8aa3b, v93
	v_rcp_f32_e32 v43, v43
	v_and_b32_e32 v36, 0xffff0000, v36
	v_cvt_pk_bf16_f32 v50, v50, v40
	v_fmac_f32_e32 v40, v56, v32
	v_mul_f32_e32 v115, v127, v115
	v_exp_f32_e32 v49, v49
	ds_write_b32 v62, v50 offset:144
	ds_write_b32 v87, v40 offset:37124
	v_cvt_pk_bf16_f32 v36, v36, v59
	v_add_f32_e32 v48, 1.0, v48
	ds_write_b32 v62, v36 offset:18576
	v_mul_f32_e32 v36, v115, v32
	v_mul_f32_e32 v40, v45, v33
	v_mul_f32_e32 v53, 0xbfb8aa3b, v94
	v_rcp_f32_e32 v48, v48
	v_rcp_f32_e32 v54, v54
	v_cvt_pk_bf16_f32 v36, v36, v40
	v_fmac_f32_e32 v40, v115, v32
	v_exp_f32_e32 v53, v53
	v_mul_f32_e32 v43, v51, v43
	v_lshlrev_b32_e32 v51, 16, v37
	ds_write_b32 v62, v36 offset:288
	ds_write_b32 v87, v40 offset:37128
	v_cvt_pk_bf16_f32 v36, v51, v60
	v_add_f32_e32 v49, 1.0, v49
	ds_write_b32 v62, v36 offset:18720
	v_mul_f32_e32 v36, v44, v32
	v_mul_f32_e32 v40, v41, v33
	v_rcp_f32_e32 v49, v49
	v_cvt_pk_bf16_f32 v36, v36, v40
	v_fmac_f32_e32 v40, v44, v32
	v_mul_f32_e32 v48, v91, v48
	v_mul_f32_e32 v54, v86, v54
	v_and_b32_e32 v37, 0xffff0000, v37
	ds_write_b32 v62, v36 offset:432
	ds_write_b32 v87, v40 offset:37132
	v_cvt_pk_bf16_f32 v36, v37, v61
	v_add_f32_e32 v53, 1.0, v53
	ds_write_b32 v62, v36 offset:18864
	v_mul_f32_e32 v36, v32, v48
	v_mul_f32_e32 v37, v33, v54
	v_rcp_f32_e32 v53, v53
	v_rcp_f32_e32 v47, v47
	v_cvt_pk_bf16_f32 v36, v36, v37
	v_fmac_f32_e32 v37, v32, v48
	v_mul_f32_e32 v49, v93, v49
	v_lshlrev_b32_e32 v55, 16, v38
	v_lshlrev_b32_e32 v63, 16, v34
	ds_write_b32 v62, v36 offset:576
	ds_write_b32 v87, v37 offset:37136
	v_cvt_pk_bf16_f32 v36, v55, v63
	ds_write_b32 v62, v36 offset:19008
	v_mul_f32_e32 v36, v32, v49
	v_mul_f32_e32 v37, v33, v42
	v_and_b32_e32 v34, 0xffff0000, v34
	v_cvt_pk_bf16_f32 v36, v36, v37
	v_fmac_f32_e32 v37, v32, v49
	v_mul_f32_e32 v53, v94, v53
	v_mul_f32_e32 v47, v57, v47
	v_and_b32_e32 v38, 0xffff0000, v38
	ds_write_b32 v62, v36 offset:720
	ds_write_b32 v87, v37 offset:37140
	v_cvt_pk_bf16_f32 v34, v38, v34
	ds_write_b32 v62, v34 offset:19152
	v_mul_f32_e32 v34, v32, v53
	v_mul_f32_e32 v36, v33, v47
	v_cvt_pk_bf16_f32 v34, v34, v36
	v_fmac_f32_e32 v36, v32, v53
	v_lshlrev_b32_e32 v57, 16, v39
	v_lshlrev_b32_e32 v86, 16, v35
	ds_write_b32 v62, v34 offset:864
	ds_write_b32 v87, v36 offset:37144
	v_cvt_pk_bf16_f32 v34, v57, v86
	ds_write_b32 v62, v34 offset:19296
	v_mul_f32_e32 v34, v32, v46
	v_mul_f32_e32 v33, v33, v43
	v_cvt_pk_bf16_f32 v34, v34, v33
	v_fmac_f32_e32 v33, v32, v46
	v_cmp_lt_i32_e64 s[0:1], s35, v2
	v_and_b32_e32 v39, 0xffff0000, v39
	v_and_b32_e32 v35, 0xffff0000, v35
	ds_write_b32 v62, v34 offset:1008
	ds_write_b32 v87, v33 offset:37148
	v_cvt_pk_bf16_f32 v32, v39, v35
	ds_write_b32 v62, v32 offset:19440
	s_waitcnt lgkmcnt(0)
	s_barrier
	s_and_saveexec_b64 s[28:29], s[0:1]
	s_xor_b64 s[0:1], exec, s[28:29]
	s_bfe_i64 s[2:3], s[22:23], 0x200000
	s_or_saveexec_b64 s[0:1], s[0:1]
	v_mov_b64_e32 v[32:33], s[2:3]
	s_xor_b64 exec, exec, s[0:1]
	s_cbranch_execz .LBB0_360
	ds_read2st64_b32 v[32:33], v3 offset0:145 offset1:147
	ds_read2st64_b32 v[34:35], v3 offset0:149 offset1:151
	ds_read2st64_b32 v[36:37], v3 offset0:153 offset1:155
	ds_read2st64_b32 v[38:39], v3 offset0:157 offset1:159
	ds_read2st64_b32 v[40:41], v3 offset0:161 offset1:163
	s_waitcnt lgkmcnt(4)
	v_add_f32_e32 v32, 0, v32
	v_add_f32_e32 v32, v32, v33
	s_waitcnt lgkmcnt(3)
	v_add_f32_e32 v32, v32, v34
	v_add_f32_e32 v32, v32, v35
	s_waitcnt lgkmcnt(2)
	v_add_f32_e32 v32, v32, v36
	v_add_f32_e32 v32, v32, v37
	s_waitcnt lgkmcnt(1)
	v_add_f32_e32 v34, v32, v38
	ds_read2st64_b32 v[32:33], v3 offset0:165 offset1:167
	v_add_f32_e32 v34, v34, v39
	s_waitcnt lgkmcnt(1)
	v_add_f32_e32 v36, v34, v40
	ds_read2st64_b32 v[34:35], v3 offset0:169 offset1:171
	v_add_f32_e32 v36, v36, v41
	s_waitcnt lgkmcnt(1)
	v_add_f32_e32 v32, v36, v32
	ds_read2st64_b32 v[36:37], v3 offset0:173 offset1:175
	v_add_f32_e32 v32, v32, v33
	s_waitcnt lgkmcnt(1)
	v_add_f32_e32 v34, v32, v34
	ds_read2st64_b32 v[32:33], v3 offset0:177 offset1:179
	v_add_f32_e32 v34, v34, v35
	s_waitcnt lgkmcnt(1)
	v_add_f32_e32 v36, v34, v36
	ds_read2st64_b32 v[34:35], v3 offset0:181 offset1:183
	v_add_f32_e32 v36, v36, v37
	s_waitcnt lgkmcnt(1)
	v_add_f32_e32 v32, v36, v32
	ds_read2st64_b32 v[36:37], v3 offset0:185 offset1:187
	v_add_f32_e32 v32, v32, v33
	s_waitcnt lgkmcnt(1)
	v_add_f32_e32 v34, v32, v34
	ds_read2st64_b32 v[32:33], v3 offset0:189 offset1:191
	v_add_f32_e32 v34, v34, v35
	s_waitcnt lgkmcnt(1)
	v_add_f32_e32 v36, v34, v36
	ds_read2st64_b32 v[34:35], v3 offset0:193 offset1:195
	v_add_f32_e32 v36, v36, v37
	s_waitcnt lgkmcnt(1)
	v_add_f32_e32 v32, v36, v32
	v_add_f32_e32 v36, v32, v33
	ds_read2st64_b32 v[32:33], v3 offset0:197 offset1:199
	s_waitcnt lgkmcnt(1)
	v_add_f32_e32 v34, v36, v34
	ds_read2st64_b32 v[36:37], v3 offset0:201 offset1:203
	v_add_f32_e32 v38, v34, v35
	ds_read2st64_b32 v[34:35], v3 offset0:205 offset1:207
	s_waitcnt lgkmcnt(2)
	v_add_f32_e32 v3, v38, v32
	v_add_f32_e32 v3, v3, v33
	s_waitcnt lgkmcnt(1)
	v_add_f32_e32 v3, v3, v36
	v_add_f32_e32 v3, v3, v37
	s_waitcnt lgkmcnt(0)
	v_add_f32_e32 v3, v3, v34
	v_add_f32_e32 v34, v3, v35
	v_ashrrev_i32_e32 v3, 31, v2
	v_lshl_add_u64 v[32:33], v[2:3], 2, s[24:25]
	global_store_dword v[32:33], v34, off
	v_mov_b64_e32 v[32:33], s[22:23]
	s_branch .LBB0_360
